# gemm_in / gemm_out tile epilogues: f32->bf16 rounding by v_cvt_pk_bf16_f32 on register pairs (two values per conversion, alternating temporaries) instead of the serial v_bfe/v_add3 bit trick per value
# speedup vs baseline: 1.0137x; 1.0046x over previous
.Lpfi_skip:
	v_add_u32_e32 v130, s1, v179
	s_movk_i32 s1, 0xa20
	v_ashrrev_i32_e32 v131, 31, v130
	v_cmp_gt_i32_e32 vcc, s1, v130
	v_lshl_add_u64 v[134:135], v[130:131], 1, s[60:61]
	s_nop 5
	v_cvt_pk_bf16_f32 v182, v112, v113
	s_barrier
	ds_write_b16 v156, v182
	ds_write_b16_d16_hi v156, v182 offset:144
	v_cvt_pk_bf16_f32 v183, v114, v115
	ds_write_b16 v156, v183 offset:288
	ds_write_b16_d16_hi v156, v183 offset:432
	v_cvt_pk_bf16_f32 v184, v116, v117
	ds_write_b16 v156, v184 offset:1152
	ds_write_b16_d16_hi v156, v184 offset:1296
	v_cvt_pk_bf16_f32 v185, v118, v119
	ds_write_b16 v156, v185 offset:1440
	ds_write_b16_d16_hi v156, v185 offset:1584
	v_cvt_pk_bf16_f32 v182, v120, v121
	ds_write_b16 v156, v182 offset:2304
	ds_write_b16_d16_hi v156, v182 offset:2448
	v_cvt_pk_bf16_f32 v183, v122, v123
	ds_write_b16 v156, v183 offset:2592
	ds_write_b16_d16_hi v156, v183 offset:2736
	v_cvt_pk_bf16_f32 v184, v124, v125
	ds_write_b16 v156, v184 offset:3456
	ds_write_b16_d16_hi v156, v184 offset:3600
	v_cvt_pk_bf16_f32 v185, v126, v127
	ds_write_b16 v156, v185 offset:3744
	ds_write_b16_d16_hi v156, v185 offset:3888
	v_cvt_pk_bf16_f32 v182, v96, v97
	ds_write_b16 v156, v182 offset:64
	ds_write_b16_d16_hi v156, v182 offset:208
	v_cvt_pk_bf16_f32 v183, v98, v99
	ds_write_b16 v156, v183 offset:352
	ds_write_b16_d16_hi v156, v183 offset:496
	v_cvt_pk_bf16_f32 v184, v100, v101
	ds_write_b16 v156, v184 offset:1216
	ds_write_b16_d16_hi v156, v184 offset:1360
	v_cvt_pk_bf16_f32 v185, v102, v103
	ds_write_b16 v156, v185 offset:1504
	ds_write_b16_d16_hi v156, v185 offset:1648
	v_cvt_pk_bf16_f32 v182, v104, v105
	ds_write_b16 v156, v182 offset:2368
	ds_write_b16_d16_hi v156, v182 offset:2512
	v_cvt_pk_bf16_f32 v183, v106, v107
	ds_write_b16 v156, v183 offset:2656
	ds_write_b16_d16_hi v156, v183 offset:2800
	v_cvt_pk_bf16_f32 v184, v108, v109
	ds_write_b16 v156, v184 offset:3520
	ds_write_b16_d16_hi v156, v184 offset:3664
	v_cvt_pk_bf16_f32 v185, v110, v111
	v_add_u32_e32 v136, s0, v153
	ds_write_b16 v156, v185 offset:3808
	ds_write_b16_d16_hi v156, v185 offset:3952
	s_and_saveexec_b64 s[0:1], vcc
	s_cbranch_execz .LBB0_242
	ds_read_b128 v[96:99], v170
	v_or_b32_e32 v100, v136, v157
	v_mad_i64_i32 v[100:101], s[10:11], v100, s33, v[134:135]
	s_waitcnt lgkmcnt(0)
	global_store_dwordx4 v[100:101], v[96:99], off
	ds_read_b128 v[96:99], v170 offset:1152
	v_or_b32_e32 v100, v136, v171
	v_mad_i64_i32 v[100:101], s[10:11], v100, s33, v[134:135]
	s_waitcnt lgkmcnt(0)
	global_store_dwordx4 v[100:101], v[96:99], off
	ds_read_b128 v[96:99], v170 offset:2304
	v_or_b32_e32 v100, v136, v252
	v_mad_i64_i32 v[100:101], s[10:11], v100, s33, v[134:135]
	s_waitcnt lgkmcnt(0)
	global_store_dwordx4 v[100:101], v[96:99], off
	ds_read_b128 v[96:99], v170 offset:3456
	v_or_b32_e32 v100, v136, v181
	v_mad_i64_i32 v[100:101], s[10:11], v100, s33, v[134:135]
	s_waitcnt lgkmcnt(0)
	global_store_dwordx4 v[100:101], v[96:99], off
.LBB0_242:
	s_or_b64 exec, exec, s[0:1]
	s_nop 0
	v_cvt_pk_bf16_f32 v182, v80, v81
	ds_write_b16 v156, v182
	ds_write_b16_d16_hi v156, v182 offset:144
	v_cvt_pk_bf16_f32 v183, v82, v83
	ds_write_b16 v156, v183 offset:288
	ds_write_b16_d16_hi v156, v183 offset:432
	v_cvt_pk_bf16_f32 v184, v84, v85
	ds_write_b16 v156, v184 offset:1152
	ds_write_b16_d16_hi v156, v184 offset:1296
	v_cvt_pk_bf16_f32 v185, v86, v87
	ds_write_b16 v156, v185 offset:1440
	ds_write_b16_d16_hi v156, v185 offset:1584
	v_cvt_pk_bf16_f32 v182, v88, v89
	ds_write_b16 v156, v182 offset:2304
	ds_write_b16_d16_hi v156, v182 offset:2448
	v_cvt_pk_bf16_f32 v183, v90, v91
	ds_write_b16 v156, v183 offset:2592
	ds_write_b16_d16_hi v156, v183 offset:2736
	v_cvt_pk_bf16_f32 v184, v92, v93
	ds_write_b16 v156, v184 offset:3456
	ds_write_b16_d16_hi v156, v184 offset:3600
	v_cvt_pk_bf16_f32 v185, v94, v95
	ds_write_b16 v156, v185 offset:3744
	ds_write_b16_d16_hi v156, v185 offset:3888
	v_cvt_pk_bf16_f32 v182, v64, v65
	ds_write_b16 v156, v182 offset:64
	ds_write_b16_d16_hi v156, v182 offset:208
	v_cvt_pk_bf16_f32 v183, v66, v67
	ds_write_b16 v156, v183 offset:352
	ds_write_b16_d16_hi v156, v183 offset:496
	v_cvt_pk_bf16_f32 v184, v68, v69
	ds_write_b16 v156, v184 offset:1216
	ds_write_b16_d16_hi v156, v184 offset:1360
	v_cvt_pk_bf16_f32 v185, v70, v71
	ds_write_b16 v156, v185 offset:1504
	ds_write_b16_d16_hi v156, v185 offset:1648
	v_cvt_pk_bf16_f32 v182, v72, v73
	ds_write_b16 v156, v182 offset:2368
	ds_write_b16_d16_hi v156, v182 offset:2512
	v_cvt_pk_bf16_f32 v183, v74, v75
	ds_write_b16 v156, v183 offset:2656
	ds_write_b16_d16_hi v156, v183 offset:2800
	v_cvt_pk_bf16_f32 v184, v76, v77
	ds_write_b16 v156, v184 offset:3520
	ds_write_b16_d16_hi v156, v184 offset:3664
	v_cvt_pk_bf16_f32 v185, v78, v79
	ds_write_b16 v156, v185 offset:3808
	ds_write_b16_d16_hi v156, v185 offset:3952
	s_and_saveexec_b64 s[0:1], vcc
	s_cbranch_execz .LBB0_244
	ds_read_b128 v[64:67], v170
	v_or_b32_e32 v70, 32, v136
	v_or_b32_e32 v68, v70, v157
	v_mad_i64_i32 v[68:69], s[10:11], v68, s33, v[134:135]
	s_waitcnt lgkmcnt(0)
	global_store_dwordx4 v[68:69], v[64:67], off
	ds_read_b128 v[64:67], v170 offset:1152
	v_or_b32_e32 v68, v70, v171
	v_mad_i64_i32 v[68:69], s[10:11], v68, s33, v[134:135]
	s_waitcnt lgkmcnt(0)
	global_store_dwordx4 v[68:69], v[64:67], off
	ds_read_b128 v[64:67], v170 offset:2304
	v_or_b32_e32 v68, v70, v252
	v_mad_i64_i32 v[68:69], s[10:11], v68, s33, v[134:135]
	s_waitcnt lgkmcnt(0)
	global_store_dwordx4 v[68:69], v[64:67], off
	ds_read_b128 v[64:67], v170 offset:3456
	v_or_b32_e32 v68, v70, v181
	v_mad_i64_i32 v[68:69], s[10:11], v68, s33, v[134:135]
	s_waitcnt lgkmcnt(0)
	global_store_dwordx4 v[68:69], v[64:67], off
.LBB0_244:
	s_or_b64 exec, exec, s[0:1]
	s_nop 0
	v_cvt_pk_bf16_f32 v182, v48, v49
	ds_write_b16 v156, v182
	ds_write_b16_d16_hi v156, v182 offset:144
	v_cvt_pk_bf16_f32 v183, v50, v51
	ds_write_b16 v156, v183 offset:288
	ds_write_b16_d16_hi v156, v183 offset:432
	v_cvt_pk_bf16_f32 v184, v52, v53
	ds_write_b16 v156, v184 offset:1152
	ds_write_b16_d16_hi v156, v184 offset:1296
	v_cvt_pk_bf16_f32 v185, v54, v55
	ds_write_b16 v156, v185 offset:1440
	ds_write_b16_d16_hi v156, v185 offset:1584
	v_cvt_pk_bf16_f32 v182, v56, v57
	ds_write_b16 v156, v182 offset:2304
	ds_write_b16_d16_hi v156, v182 offset:2448
	v_cvt_pk_bf16_f32 v183, v58, v59
	ds_write_b16 v156, v183 offset:2592
	ds_write_b16_d16_hi v156, v183 offset:2736
	v_cvt_pk_bf16_f32 v184, v60, v61
	ds_write_b16 v156, v184 offset:3456
	ds_write_b16_d16_hi v156, v184 offset:3600
	v_cvt_pk_bf16_f32 v185, v62, v63
	ds_write_b16 v156, v185 offset:3744
	ds_write_b16_d16_hi v156, v185 offset:3888
	v_cvt_pk_bf16_f32 v182, v32, v33
	ds_write_b16 v156, v182 offset:64
	ds_write_b16_d16_hi v156, v182 offset:208
	v_cvt_pk_bf16_f32 v183, v34, v35
	ds_write_b16 v156, v183 offset:352
	ds_write_b16_d16_hi v156, v183 offset:496
	v_cvt_pk_bf16_f32 v184, v36, v37
	ds_write_b16 v156, v184 offset:1216
	ds_write_b16_d16_hi v156, v184 offset:1360
	v_cvt_pk_bf16_f32 v185, v38, v39
	ds_write_b16 v156, v185 offset:1504
	ds_write_b16_d16_hi v156, v185 offset:1648
	v_cvt_pk_bf16_f32 v182, v40, v41
	ds_write_b16 v156, v182 offset:2368
	ds_write_b16_d16_hi v156, v182 offset:2512
	v_cvt_pk_bf16_f32 v183, v42, v43
	ds_write_b16 v156, v183 offset:2656
	ds_write_b16_d16_hi v156, v183 offset:2800
	v_cvt_pk_bf16_f32 v184, v44, v45
	ds_write_b16 v156, v184 offset:3520
	ds_write_b16_d16_hi v156, v184 offset:3664
	v_cvt_pk_bf16_f32 v185, v46, v47
	ds_write_b16 v156, v185 offset:3808
	ds_write_b16_d16_hi v156, v185 offset:3952
	s_and_saveexec_b64 s[0:1], vcc
	s_cbranch_execz .LBB0_246
	ds_read_b128 v[32:35], v170
	v_or_b32_e32 v38, 64, v136
	v_or_b32_e32 v36, v38, v157
	v_mad_i64_i32 v[36:37], s[10:11], v36, s33, v[134:135]
	s_waitcnt lgkmcnt(0)
	global_store_dwordx4 v[36:37], v[32:35], off
	ds_read_b128 v[32:35], v170 offset:1152
	v_or_b32_e32 v36, v38, v171
	v_mad_i64_i32 v[36:37], s[10:11], v36, s33, v[134:135]
	s_waitcnt lgkmcnt(0)
	global_store_dwordx4 v[36:37], v[32:35], off
	ds_read_b128 v[32:35], v170 offset:2304
	v_or_b32_e32 v36, v38, v252
	v_mad_i64_i32 v[36:37], s[10:11], v36, s33, v[134:135]
	s_waitcnt lgkmcnt(0)
	global_store_dwordx4 v[36:37], v[32:35], off
	ds_read_b128 v[32:35], v170 offset:3456
	v_or_b32_e32 v36, v38, v181
	v_mad_i64_i32 v[36:37], s[10:11], v36, s33, v[134:135]
	s_waitcnt lgkmcnt(0)
	global_store_dwordx4 v[36:37], v[32:35], off
.LBB0_246:
	s_or_b64 exec, exec, s[0:1]
	s_nop 0
	v_cvt_pk_bf16_f32 v182, v16, v17
	ds_write_b16 v156, v182
	ds_write_b16_d16_hi v156, v182 offset:144
	v_cvt_pk_bf16_f32 v183, v18, v19
	ds_write_b16 v156, v183 offset:288
	ds_write_b16_d16_hi v156, v183 offset:432
	v_cvt_pk_bf16_f32 v184, v20, v21
	ds_write_b16 v156, v184 offset:1152
	ds_write_b16_d16_hi v156, v184 offset:1296
	v_cvt_pk_bf16_f32 v185, v22, v23
	ds_write_b16 v156, v185 offset:1440
	ds_write_b16_d16_hi v156, v185 offset:1584
	v_cvt_pk_bf16_f32 v182, v24, v25
	ds_write_b16 v156, v182 offset:2304
	ds_write_b16_d16_hi v156, v182 offset:2448
	v_cvt_pk_bf16_f32 v183, v26, v27
	ds_write_b16 v156, v183 offset:2592
	ds_write_b16_d16_hi v156, v183 offset:2736
	v_cvt_pk_bf16_f32 v184, v28, v29
	ds_write_b16 v156, v184 offset:3456
	ds_write_b16_d16_hi v156, v184 offset:3600
	v_cvt_pk_bf16_f32 v185, v30, v31
	ds_write_b16 v156, v185 offset:3744
	ds_write_b16_d16_hi v156, v185 offset:3888
	v_cvt_pk_bf16_f32 v182, v0, v1
	ds_write_b16 v156, v182 offset:64
	ds_write_b16_d16_hi v156, v182 offset:208
	v_cvt_pk_bf16_f32 v183, v2, v3
	ds_write_b16 v156, v183 offset:352
	ds_write_b16_d16_hi v156, v183 offset:496
	v_cvt_pk_bf16_f32 v184, v4, v5
	ds_write_b16 v156, v184 offset:1216
	ds_write_b16_d16_hi v156, v184 offset:1360
	v_cvt_pk_bf16_f32 v185, v6, v7
	ds_write_b16 v156, v185 offset:1504
	ds_write_b16_d16_hi v156, v185 offset:1648
	v_cvt_pk_bf16_f32 v182, v8, v9
	ds_write_b16 v156, v182 offset:2368
	ds_write_b16_d16_hi v156, v182 offset:2512
	v_cvt_pk_bf16_f32 v183, v10, v11
	ds_write_b16 v156, v183 offset:2656
	ds_write_b16_d16_hi v156, v183 offset:2800
	v_cvt_pk_bf16_f32 v184, v12, v13
	ds_write_b16 v156, v184 offset:3520
	ds_write_b16_d16_hi v156, v184 offset:3664
	v_cvt_pk_bf16_f32 v185, v14, v15
	ds_write_b16 v156, v185 offset:3808
	ds_write_b16_d16_hi v156, v185 offset:3952
	s_and_saveexec_b64 s[0:1], vcc
	s_cbranch_execz .LBB0_237
	ds_read_b128 v[0:3], v170
	v_or_b32_e32 v6, 0x60, v136
	v_or_b32_e32 v4, v6, v157
	v_mad_i64_i32 v[4:5], s[10:11], v4, s33, v[134:135]
	s_waitcnt lgkmcnt(0)
	global_store_dwordx4 v[4:5], v[0:3], off
	ds_read_b128 v[0:3], v170 offset:1152
	v_or_b32_e32 v4, v6, v171
	v_mad_i64_i32 v[4:5], s[10:11], v4, s33, v[134:135]
	s_waitcnt lgkmcnt(0)
	global_store_dwordx4 v[4:5], v[0:3], off
	ds_read_b128 v[0:3], v170 offset:2304
	v_or_b32_e32 v4, v6, v252
	v_mad_i64_i32 v[4:5], s[10:11], v4, s33, v[134:135]
	s_waitcnt lgkmcnt(0)
	global_store_dwordx4 v[4:5], v[0:3], off
	ds_read_b128 v[0:3], v170 offset:3456
	v_or_b32_e32 v4, v6, v181
	v_mad_i64_i32 v[4:5], s[10:11], v4, s33, v[134:135]
	s_waitcnt lgkmcnt(0)
	global_store_dwordx4 v[4:5], v[0:3], off
	s_branch .LBB0_237

.Lpfg_skip:
	v_add_u32_e32 v130, s1, v179
	s_movk_i32 s1, 0x7fff
	v_ashrrev_i32_e32 v131, 31, v130
	v_cmp_gt_i32_e32 vcc, s1, v130
	v_lshl_add_u64 v[134:135], v[130:131], 1, s[86:87]
	s_nop 5
	v_cvt_pk_bf16_f32 v182, v112, v113
	s_barrier
	ds_write_b16 v156, v182
	ds_write_b16_d16_hi v156, v182 offset:144
	v_cvt_pk_bf16_f32 v183, v114, v115
	ds_write_b16 v156, v183 offset:288
	ds_write_b16_d16_hi v156, v183 offset:432
	v_cvt_pk_bf16_f32 v184, v116, v117
	ds_write_b16 v156, v184 offset:1152
	ds_write_b16_d16_hi v156, v184 offset:1296
	v_cvt_pk_bf16_f32 v185, v118, v119
	ds_write_b16 v156, v185 offset:1440
	ds_write_b16_d16_hi v156, v185 offset:1584
	v_cvt_pk_bf16_f32 v182, v120, v121
	ds_write_b16 v156, v182 offset:2304
	ds_write_b16_d16_hi v156, v182 offset:2448
	v_cvt_pk_bf16_f32 v183, v122, v123
	ds_write_b16 v156, v183 offset:2592
	ds_write_b16_d16_hi v156, v183 offset:2736
	v_cvt_pk_bf16_f32 v184, v124, v125
	ds_write_b16 v156, v184 offset:3456
	ds_write_b16_d16_hi v156, v184 offset:3600
	v_cvt_pk_bf16_f32 v185, v126, v127
	ds_write_b16 v156, v185 offset:3744
	ds_write_b16_d16_hi v156, v185 offset:3888
	v_cvt_pk_bf16_f32 v182, v96, v97
	ds_write_b16 v156, v182 offset:64
	ds_write_b16_d16_hi v156, v182 offset:208
	v_cvt_pk_bf16_f32 v183, v98, v99
	ds_write_b16 v156, v183 offset:352
	ds_write_b16_d16_hi v156, v183 offset:496
	v_cvt_pk_bf16_f32 v184, v100, v101
	ds_write_b16 v156, v184 offset:1216
	ds_write_b16_d16_hi v156, v184 offset:1360
	v_cvt_pk_bf16_f32 v185, v102, v103
	ds_write_b16 v156, v185 offset:1504
	ds_write_b16_d16_hi v156, v185 offset:1648
	v_cvt_pk_bf16_f32 v182, v104, v105
	ds_write_b16 v156, v182 offset:2368
	ds_write_b16_d16_hi v156, v182 offset:2512
	v_cvt_pk_bf16_f32 v183, v106, v107
	ds_write_b16 v156, v183 offset:2656
	ds_write_b16_d16_hi v156, v183 offset:2800
	v_cvt_pk_bf16_f32 v184, v108, v109
	ds_write_b16 v156, v184 offset:3520
	ds_write_b16_d16_hi v156, v184 offset:3664
	v_cvt_pk_bf16_f32 v185, v110, v111
	v_add_u32_e32 v136, s0, v153
	ds_write_b16 v156, v185 offset:3808
	ds_write_b16_d16_hi v156, v185 offset:3952
	s_and_saveexec_b64 s[0:1], vcc
	s_cbranch_execz .Lgo_242
	ds_read_b128 v[96:99], v170
	v_or_b32_e32 v100, v136, v157
	v_mad_i64_i32 v[100:101], s[10:11], v100, s88, v[134:135]
	s_waitcnt lgkmcnt(0)
	global_store_dwordx4 v[100:101], v[96:99], off
	ds_read_b128 v[96:99], v170 offset:1152
	v_or_b32_e32 v100, v136, v171
	v_mad_i64_i32 v[100:101], s[10:11], v100, s88, v[134:135]
	s_waitcnt lgkmcnt(0)
	global_store_dwordx4 v[100:101], v[96:99], off
	ds_read_b128 v[96:99], v170 offset:2304
	v_or_b32_e32 v100, v136, v252
	v_mad_i64_i32 v[100:101], s[10:11], v100, s88, v[134:135]
	s_waitcnt lgkmcnt(0)
	global_store_dwordx4 v[100:101], v[96:99], off
	ds_read_b128 v[96:99], v170 offset:3456
	v_or_b32_e32 v100, v136, v181
	v_mad_i64_i32 v[100:101], s[10:11], v100, s88, v[134:135]
	s_waitcnt lgkmcnt(0)
	global_store_dwordx4 v[100:101], v[96:99], off
.Lgo_242:
	s_or_b64 exec, exec, s[0:1]
	s_nop 0
	v_cvt_pk_bf16_f32 v182, v80, v81
	ds_write_b16 v156, v182
	ds_write_b16_d16_hi v156, v182 offset:144
	v_cvt_pk_bf16_f32 v183, v82, v83
	ds_write_b16 v156, v183 offset:288
	ds_write_b16_d16_hi v156, v183 offset:432
	v_cvt_pk_bf16_f32 v184, v84, v85
	ds_write_b16 v156, v184 offset:1152
	ds_write_b16_d16_hi v156, v184 offset:1296
	v_cvt_pk_bf16_f32 v185, v86, v87
	ds_write_b16 v156, v185 offset:1440
	ds_write_b16_d16_hi v156, v185 offset:1584
	v_cvt_pk_bf16_f32 v182, v88, v89
	ds_write_b16 v156, v182 offset:2304
	ds_write_b16_d16_hi v156, v182 offset:2448
	v_cvt_pk_bf16_f32 v183, v90, v91
	ds_write_b16 v156, v183 offset:2592
	ds_write_b16_d16_hi v156, v183 offset:2736
	v_cvt_pk_bf16_f32 v184, v92, v93
	ds_write_b16 v156, v184 offset:3456
	ds_write_b16_d16_hi v156, v184 offset:3600
	v_cvt_pk_bf16_f32 v185, v94, v95
	ds_write_b16 v156, v185 offset:3744
	ds_write_b16_d16_hi v156, v185 offset:3888
	v_cvt_pk_bf16_f32 v182, v64, v65
	ds_write_b16 v156, v182 offset:64
	ds_write_b16_d16_hi v156, v182 offset:208
	v_cvt_pk_bf16_f32 v183, v66, v67
	ds_write_b16 v156, v183 offset:352
	ds_write_b16_d16_hi v156, v183 offset:496
	v_cvt_pk_bf16_f32 v184, v68, v69
	ds_write_b16 v156, v184 offset:1216
	ds_write_b16_d16_hi v156, v184 offset:1360
	v_cvt_pk_bf16_f32 v185, v70, v71
	ds_write_b16 v156, v185 offset:1504
	ds_write_b16_d16_hi v156, v185 offset:1648
	v_cvt_pk_bf16_f32 v182, v72, v73
	ds_write_b16 v156, v182 offset:2368
	ds_write_b16_d16_hi v156, v182 offset:2512
	v_cvt_pk_bf16_f32 v183, v74, v75
	ds_write_b16 v156, v183 offset:2656
	ds_write_b16_d16_hi v156, v183 offset:2800
	v_cvt_pk_bf16_f32 v184, v76, v77
	ds_write_b16 v156, v184 offset:3520
	ds_write_b16_d16_hi v156, v184 offset:3664
	v_cvt_pk_bf16_f32 v185, v78, v79
	ds_write_b16 v156, v185 offset:3808
	ds_write_b16_d16_hi v156, v185 offset:3952
	s_and_saveexec_b64 s[0:1], vcc
	s_cbranch_execz .Lgo_244
	ds_read_b128 v[64:67], v170
	v_or_b32_e32 v70, 32, v136
	v_or_b32_e32 v68, v70, v157
	v_mad_i64_i32 v[68:69], s[10:11], v68, s88, v[134:135]
	s_waitcnt lgkmcnt(0)
	global_store_dwordx4 v[68:69], v[64:67], off
	ds_read_b128 v[64:67], v170 offset:1152
	v_or_b32_e32 v68, v70, v171
	v_mad_i64_i32 v[68:69], s[10:11], v68, s88, v[134:135]
	s_waitcnt lgkmcnt(0)
	global_store_dwordx4 v[68:69], v[64:67], off
	ds_read_b128 v[64:67], v170 offset:2304
	v_or_b32_e32 v68, v70, v252
	v_mad_i64_i32 v[68:69], s[10:11], v68, s88, v[134:135]
	s_waitcnt lgkmcnt(0)
	global_store_dwordx4 v[68:69], v[64:67], off
	ds_read_b128 v[64:67], v170 offset:3456
	v_or_b32_e32 v68, v70, v181
	v_mad_i64_i32 v[68:69], s[10:11], v68, s88, v[134:135]
	s_waitcnt lgkmcnt(0)
	global_store_dwordx4 v[68:69], v[64:67], off
.Lgo_244:
	s_or_b64 exec, exec, s[0:1]
	s_nop 0
	v_cvt_pk_bf16_f32 v182, v48, v49
	ds_write_b16 v156, v182
	ds_write_b16_d16_hi v156, v182 offset:144
	v_cvt_pk_bf16_f32 v183, v50, v51
	ds_write_b16 v156, v183 offset:288
	ds_write_b16_d16_hi v156, v183 offset:432
	v_cvt_pk_bf16_f32 v184, v52, v53
	ds_write_b16 v156, v184 offset:1152
	ds_write_b16_d16_hi v156, v184 offset:1296
	v_cvt_pk_bf16_f32 v185, v54, v55
	ds_write_b16 v156, v185 offset:1440
	ds_write_b16_d16_hi v156, v185 offset:1584
	v_cvt_pk_bf16_f32 v182, v56, v57
	ds_write_b16 v156, v182 offset:2304
	ds_write_b16_d16_hi v156, v182 offset:2448
	v_cvt_pk_bf16_f32 v183, v58, v59
	ds_write_b16 v156, v183 offset:2592
	ds_write_b16_d16_hi v156, v183 offset:2736
	v_cvt_pk_bf16_f32 v184, v60, v61
	ds_write_b16 v156, v184 offset:3456
	ds_write_b16_d16_hi v156, v184 offset:3600
	v_cvt_pk_bf16_f32 v185, v62, v63
	ds_write_b16 v156, v185 offset:3744
	ds_write_b16_d16_hi v156, v185 offset:3888
	v_cvt_pk_bf16_f32 v182, v32, v33
	ds_write_b16 v156, v182 offset:64
	ds_write_b16_d16_hi v156, v182 offset:208
	v_cvt_pk_bf16_f32 v183, v34, v35
	ds_write_b16 v156, v183 offset:352
	ds_write_b16_d16_hi v156, v183 offset:496
	v_cvt_pk_bf16_f32 v184, v36, v37
	ds_write_b16 v156, v184 offset:1216
	ds_write_b16_d16_hi v156, v184 offset:1360
	v_cvt_pk_bf16_f32 v185, v38, v39
	ds_write_b16 v156, v185 offset:1504
	ds_write_b16_d16_hi v156, v185 offset:1648
	v_cvt_pk_bf16_f32 v182, v40, v41
	ds_write_b16 v156, v182 offset:2368
	ds_write_b16_d16_hi v156, v182 offset:2512
	v_cvt_pk_bf16_f32 v183, v42, v43
	ds_write_b16 v156, v183 offset:2656
	ds_write_b16_d16_hi v156, v183 offset:2800
	v_cvt_pk_bf16_f32 v184, v44, v45
	ds_write_b16 v156, v184 offset:3520
	ds_write_b16_d16_hi v156, v184 offset:3664
	v_cvt_pk_bf16_f32 v185, v46, v47
	ds_write_b16 v156, v185 offset:3808
	ds_write_b16_d16_hi v156, v185 offset:3952
	s_and_saveexec_b64 s[0:1], vcc
	s_cbranch_execz .Lgo_246
	ds_read_b128 v[32:35], v170
	v_or_b32_e32 v38, 64, v136
	v_or_b32_e32 v36, v38, v157
	v_mad_i64_i32 v[36:37], s[10:11], v36, s88, v[134:135]
	s_waitcnt lgkmcnt(0)
	global_store_dwordx4 v[36:37], v[32:35], off
	ds_read_b128 v[32:35], v170 offset:1152
	v_or_b32_e32 v36, v38, v171
	v_mad_i64_i32 v[36:37], s[10:11], v36, s88, v[134:135]
	s_waitcnt lgkmcnt(0)
	global_store_dwordx4 v[36:37], v[32:35], off
	ds_read_b128 v[32:35], v170 offset:2304
	v_or_b32_e32 v36, v38, v252
	v_mad_i64_i32 v[36:37], s[10:11], v36, s88, v[134:135]
	s_waitcnt lgkmcnt(0)
	global_store_dwordx4 v[36:37], v[32:35], off
	ds_read_b128 v[32:35], v170 offset:3456
	v_or_b32_e32 v36, v38, v181
	v_mad_i64_i32 v[36:37], s[10:11], v36, s88, v[134:135]
	s_waitcnt lgkmcnt(0)
	global_store_dwordx4 v[36:37], v[32:35], off
.Lgo_246:
	s_or_b64 exec, exec, s[0:1]
	s_nop 0
	v_cvt_pk_bf16_f32 v182, v16, v17
	ds_write_b16 v156, v182
	ds_write_b16_d16_hi v156, v182 offset:144
	v_cvt_pk_bf16_f32 v183, v18, v19
	ds_write_b16 v156, v183 offset:288
	ds_write_b16_d16_hi v156, v183 offset:432
	v_cvt_pk_bf16_f32 v184, v20, v21
	ds_write_b16 v156, v184 offset:1152
	ds_write_b16_d16_hi v156, v184 offset:1296
	v_cvt_pk_bf16_f32 v185, v22, v23
	ds_write_b16 v156, v185 offset:1440
	ds_write_b16_d16_hi v156, v185 offset:1584
	v_cvt_pk_bf16_f32 v182, v24, v25
	ds_write_b16 v156, v182 offset:2304
	ds_write_b16_d16_hi v156, v182 offset:2448
	v_cvt_pk_bf16_f32 v183, v26, v27
	ds_write_b16 v156, v183 offset:2592
	ds_write_b16_d16_hi v156, v183 offset:2736
	v_cvt_pk_bf16_f32 v184, v28, v29
	ds_write_b16 v156, v184 offset:3456
	ds_write_b16_d16_hi v156, v184 offset:3600
	v_cvt_pk_bf16_f32 v185, v30, v31
	ds_write_b16 v156, v185 offset:3744
	ds_write_b16_d16_hi v156, v185 offset:3888
	v_cvt_pk_bf16_f32 v182, v0, v1
	ds_write_b16 v156, v182 offset:64
	ds_write_b16_d16_hi v156, v182 offset:208
	v_cvt_pk_bf16_f32 v183, v2, v3
	ds_write_b16 v156, v183 offset:352
	ds_write_b16_d16_hi v156, v183 offset:496
	v_cvt_pk_bf16_f32 v184, v4, v5
	ds_write_b16 v156, v184 offset:1216
	ds_write_b16_d16_hi v156, v184 offset:1360
	v_cvt_pk_bf16_f32 v185, v6, v7
	ds_write_b16 v156, v185 offset:1504
	ds_write_b16_d16_hi v156, v185 offset:1648
	v_cvt_pk_bf16_f32 v182, v8, v9
	ds_write_b16 v156, v182 offset:2368
	ds_write_b16_d16_hi v156, v182 offset:2512
	v_cvt_pk_bf16_f32 v183, v10, v11
	ds_write_b16 v156, v183 offset:2656
	ds_write_b16_d16_hi v156, v183 offset:2800
	v_cvt_pk_bf16_f32 v184, v12, v13
	ds_write_b16 v156, v184 offset:3520
	ds_write_b16_d16_hi v156, v184 offset:3664
	v_cvt_pk_bf16_f32 v185, v14, v15
	ds_write_b16 v156, v185 offset:3808
	ds_write_b16_d16_hi v156, v185 offset:3952
	s_and_saveexec_b64 s[0:1], vcc
	s_cbranch_execz .Lgo_237
	ds_read_b128 v[0:3], v170
	v_or_b32_e32 v6, 0x60, v136
	v_or_b32_e32 v4, v6, v157
	v_mad_i64_i32 v[4:5], s[10:11], v4, s88, v[134:135]
	s_waitcnt lgkmcnt(0)
	global_store_dwordx4 v[4:5], v[0:3], off
	ds_read_b128 v[0:3], v170 offset:1152
	v_or_b32_e32 v4, v6, v171
	v_mad_i64_i32 v[4:5], s[10:11], v4, s88, v[134:135]
	s_waitcnt lgkmcnt(0)
	global_store_dwordx4 v[4:5], v[0:3], off
	ds_read_b128 v[0:3], v170 offset:2304
	v_or_b32_e32 v4, v6, v252
	v_mad_i64_i32 v[4:5], s[10:11], v4, s88, v[134:135]
	s_waitcnt lgkmcnt(0)
	global_store_dwordx4 v[4:5], v[0:3], off
	ds_read_b128 v[0:3], v170 offset:3456
	v_or_b32_e32 v4, v6, v181
	v_mad_i64_i32 v[4:5], s[10:11], v4, s88, v[134:135]
	s_waitcnt lgkmcnt(0)
	global_store_dwordx4 v[4:5], v[0:3], off
	s_branch .Lgo_237
